# v34
# baseline (speedup 1.0000x reference)
.LBB0_230:
	s_or_b32 s9, s8, s10
	v_lshl_add_u32 v28, s9, 6, v27
	v_mov_b64_e32 v[2:3], s[6:7]
	v_mad_i64_i32 v[2:3], s[22:23], v28, s86, v[2:3]
	s_mov_b32 s22, 0x30000
	s_mov_b32 s23, 0
	v_lshl_add_u64 v[46:47], v[2:3], 0, s[22:23]
	s_cmp_lg_u32 s8, 0
	s_cbranch_scc1 .Ls5a_pf_have
	global_load_dwordx4 v[38:41], v[2:3], off
	global_load_dwordx4 v[42:45], v[2:3], off offset:16
	s_waitcnt vmcnt(0)
	s_branch .Ls5a_pf_go
.Ls5a_pf_have:
	s_waitcnt vmcnt(1)
.Ls5a_pf_go:
	v_mov_b32_e32 v2, 0
	s_mov_b32 s22, 0
	v_mov_b32_e32 v3, v2
	ds_write_b128 v13, v[38:41]
	ds_write_b128 v13, v[42:45] offset:16
	s_waitcnt lgkmcnt(0)
	s_cmp_eq_u32 s8, 3
	s_cbranch_scc1 .Ls5a_pf_none
	global_load_dwordx4 v[38:41], v[46:47], off
	global_load_dwordx4 v[42:45], v[46:47], off offset:16
.Ls5a_pf_none:
	v_mov_b32_e32 v228, v0
	v_mov_b32_e32 v229, v14
	v_mov_b32_e32 v230, v17
	v_mov_b32_e32 v231, v18
	v_mov_b32_e32 v232, v21
	v_mov_b32_e32 v233, v22
	v_mov_b32_e32 v234, v4
	v_mov_b32_e32 v235, v5
	v_mov_b32_e32 v236, v15
	v_mov_b32_e32 v237, v16
	v_mov_b32_e32 v238, v19
	v_mov_b32_e32 v239, v20
	v_mov_b32_e32 v240, v23
	v_mov_b32_e32 v241, v24
	v_mov_b32_e32 v242, v25
	v_mov_b32_e32 v243, v26
	v_and_b32_e32 v252, 3, v178
	v_lshlrev_b32_e32 v252, 5, v252
